# conv: all 40 per-item weight/bias loads issued upfront with the u loads (24 into spare VGPRs, 6 deferred after k0 FMAs), copies at use sites, waits recounted
# baseline (speedup 1.0000x reference)
; DI float bflo(unsigned w) { return __uint_as_float(w << 16); }
; DI float bfhi(unsigned w) { return __uint_as_float(w & 0xffff0000u); }
; DI float silu_f(float g) { return g * __builtin_amdgcn_rcpf(1.0f + __expf(-g)); }
; DI void conv_phase(PPtr p, int j, ldsp lds, int tid) {
;     ...
;         for (int k = 0; k < 4; ++k) {
;             const int cl = (cgp + 8 * k) * 8, ch0 = cb * 256 + cl;
;             float acc[8];
;             { const f32x4 b0 = *(const f32x4*)(cbias + ch0), b1 = *(const f32x4*)(cbias + ch0 + 4);
; #pragma unroll
;               for (int i = 0; i < 4; ++i) { acc[i] = b0[i]; acc[4 + i] = b1[i]; } }
; #pragma unroll
;             for (int w = 0; w < 4; ++w) {
;                 const f32x4 w0 = *(const f32x4*)(cw + w * CONVD + ch0), w1 = *(const f32x4*)(cw + w * CONVD + ch0 + 4);
;                 const u32x4 uu = u[k][w];
;                 acc[0] += bflo(uu[0]) * w0[0]; acc[1] += bfhi(uu[0]) * w0[1]; acc[2] += bflo(uu[1]) * w0[2]; acc[3] += bfhi(uu[1]) * w0[3];
;                 acc[4] += bflo(uu[2]) * w1[0]; acc[5] += bfhi(uu[2]) * w1[1]; acc[6] += bflo(uu[3]) * w1[2]; acc[7] += bfhi(uu[3]) * w1[3];
;             }
; #pragma unroll
;             for (int i = 0; i < 8; ++i) acc[i] = silu_f(acc[i]);
.LBB0_545:
	s_or_b64 exec, exec, s[0:1]
	v_lshlrev_b64 v[66:67], 2, v[66:67]
	v_lshl_add_u64 v[132:133], s[12:13], 0, v[66:67]
	v_lshl_add_u64 v[134:135], s[2:3], 0, v[66:67]
	s_mov_b64 s[0:1], 0x3000
	v_lshl_add_u64 v[126:127], v[134:135], 0, s[0:1]
	s_mov_b64 s[0:1], 0x6000
	v_lshl_add_u64 v[128:129], v[134:135], 0, s[0:1]
	s_mov_b64 s[0:1], 0x9000
	v_lshl_add_u64 v[130:131], v[134:135], 0, s[0:1]
	global_load_dwordx4 v[90:93], v[132:133], off offset:16
	global_load_dwordx4 v[94:97], v[132:133], off
	global_load_dwordx4 v[98:101], v[134:135], off offset:16
	global_load_dwordx4 v[102:105], v[134:135], off
	global_load_dwordx4 v[106:109], v[126:127], off
	global_load_dwordx4 v[110:113], v[126:127], off offset:16
	global_load_dwordx4 v[114:117], v[128:129], off
	global_load_dwordx4 v[118:121], v[130:131], off
	global_load_dwordx4 v[122:125], v[128:129], off offset:16
	global_load_dwordx4 v[66:69], v[130:131], off offset:16
	global_load_dwordx4 v[144:147], v[132:133], off offset:272
	global_load_dwordx4 v[148:151], v[132:133], off offset:256
	global_load_dwordx4 v[156:159], v[134:135], off offset:272
	global_load_dwordx4 v[160:163], v[134:135], off offset:256
	global_load_dwordx4 v[164:167], v[126:127], off offset:256
	global_load_dwordx4 v[168:171], v[126:127], off offset:272
	global_load_dwordx4 v[172:175], v[128:129], off offset:256
	global_load_dwordx4 v[176:179], v[128:129], off offset:272
	global_load_dwordx4 v[180:183], v[130:131], off offset:256
	global_load_dwordx4 v[184:187], v[130:131], off offset:272
	global_load_dwordx4 v[188:191], v[132:133], off offset:528
	global_load_dwordx4 v[192:195], v[132:133], off offset:512
	global_load_dwordx4 v[196:199], v[134:135], off offset:528
	global_load_dwordx4 v[206:209], v[134:135], off offset:512
	global_load_dwordx4 v[210:213], v[126:127], off offset:512
	global_load_dwordx4 v[218:221], v[126:127], off offset:528
	global_load_dwordx4 v[222:225], v[128:129], off offset:512
	global_load_dwordx4 v[226:229], v[128:129], off offset:528
	global_load_dwordx4 v[230:233], v[130:131], off offset:512
	global_load_dwordx4 v[234:237], v[130:131], off offset:528
	global_load_dwordx4 v[238:241], v[128:129], off offset:768
	global_load_dwordx4 v[242:245], v[128:129], off offset:784
	global_load_dwordx4 v[246:249], v[130:131], off offset:768
	global_load_dwordx4 v[250:253], v[130:131], off offset:784
	v_lshlrev_b64 v[82:83], 10, v[82:83]
	s_waitcnt vmcnt(34)
	v_lshlrev_b32_e32 v126, 16, v58
	v_and_b32_e32 v127, 0xffff0000, v58
	v_lshlrev_b32_e32 v128, 16, v54
	v_and_b32_e32 v129, 0xffff0000, v54
	v_lshlrev_b32_e32 v132, 16, v50
	v_and_b32_e32 v133, 0xffff0000, v50
	v_lshlrev_b32_e32 v58, 16, v59
	v_and_b32_e32 v59, 0xffff0000, v59
	v_lshlrev_b32_e32 v136, 16, v51
	v_and_b32_e32 v137, 0xffff0000, v51
	v_lshl_add_u64 v[50:51], s[10:11], 0, v[82:83]
	v_lshlrev_b32_e32 v130, 16, v62
	v_and_b32_e32 v131, 0xffff0000, v62
	v_lshlrev_b32_e32 v134, 16, v55
	v_and_b32_e32 v135, 0xffff0000, v55
	v_lshlrev_b32_e32 v62, 16, v63
	v_and_b32_e32 v63, 0xffff0000, v63
	v_lshlrev_b32_e32 v138, 16, v60
	v_and_b32_e32 v139, 0xffff0000, v60
	v_lshlrev_b32_e32 v60, 16, v61
	v_and_b32_e32 v61, 0xffff0000, v61
	v_lshlrev_b32_e32 v140, 16, v56
	v_and_b32_e32 v141, 0xffff0000, v56
	v_lshlrev_b32_e32 v56, 16, v57
	v_and_b32_e32 v57, 0xffff0000, v57
	v_lshlrev_b32_e32 v142, 16, v64
	v_and_b32_e32 v143, 0xffff0000, v64
	s_mul_i32 s4, s22, -12
	s_add_i32 s8, s20, s4
	s_mov_b32 s15, s97
	s_cmp_gt_i32 s8, 7
	s_mov_b64 s[0:1], 0x1c43ec00
	s_mov_b64 s[6:7], 0x1b43f000
	v_lshl_add_u64 v[54:55], s[14:15], 1, v[50:51]
	s_cselect_b64 s[4:5], -1, 0
	s_cmp_lt_u32 s8, 10
	v_lshl_add_u64 v[50:51], v[54:55], 0, s[0:1]
	v_lshl_add_u64 v[54:55], v[54:55], 0, s[6:7]
	s_cselect_b64 vcc, -1, 0
	s_cmp_lt_i32 s8, 8
	v_cndmask_b32_e32 v51, v51, v55, vcc
	v_cndmask_b32_e32 v50, v50, v54, vcc
	s_waitcnt vmcnt(31)
	v_pk_fma_f32 v[90:91], v[98:99], v[138:139], v[90:91]
	s_waitcnt vmcnt(30)
	v_pk_fma_f32 v[82:83], v[102:103], v[126:127], v[94:95]
	v_pk_fma_f32 v[58:59], v[104:105], v[58:59], v[96:97]
	s_waitcnt vmcnt(29)
	v_pk_fma_f32 v[82:83], v[106:107], v[128:129], v[82:83]
	v_pk_fma_f32 v[58:59], v[108:109], v[134:135], v[58:59]
	v_pk_fma_f32 v[60:61], v[100:101], v[60:61], v[92:93]
	s_waitcnt vmcnt(28)
	v_pk_fma_f32 v[90:91], v[110:111], v[140:141], v[90:91]
	v_pk_fma_f32 v[56:57], v[112:113], v[56:57], v[60:61]
	v_lshlrev_b32_e32 v60, 16, v65
	v_and_b32_e32 v61, 0xffff0000, v65
	s_waitcnt vmcnt(27)
	v_pk_fma_f32 v[82:83], v[114:115], v[130:131], v[82:83]
	v_pk_fma_f32 v[62:63], v[116:117], v[62:63], v[58:59]
	s_waitcnt vmcnt(26)
	v_pk_fma_f32 v[58:59], v[118:119], v[132:133], v[82:83]
	s_nop 0
	v_mul_f32_e32 v0, 0xbfb8aa3b, v58
	v_pk_fma_f32 v[62:63], v[120:121], v[136:137], v[62:63]
	s_waitcnt vmcnt(25)
	v_pk_fma_f32 v[82:83], v[122:123], v[142:143], v[90:91]
	v_lshlrev_b32_e32 v90, 16, v52
	v_and_b32_e32 v91, 0xffff0000, v52
	v_pk_fma_f32 v[56:57], v[124:125], v[60:61], v[56:57]
	v_lshlrev_b32_e32 v52, 16, v53
	v_and_b32_e32 v53, 0xffff0000, v53
	v_exp_f32_e32 v0, v0
	v_mul_f32_e32 v60, 0xbfb8aa3b, v59
	v_exp_f32_e32 v64, v60
	s_waitcnt vmcnt(24)
	v_pk_fma_f32 v[60:61], v[68:69], v[52:53], v[56:57]
	v_mul_f32_e32 v53, 0xbfb8aa3b, v62
	v_exp_f32_e32 v56, v53
	v_mul_f32_e32 v53, 0xbfb8aa3b, v63
	v_exp_f32_e32 v57, v53
	v_add_f32_e32 v0, 1.0, v0
	v_rcp_f32_e32 v52, v0
	v_add_f32_e32 v0, 1.0, v64
	v_pk_fma_f32 v[66:67], v[66:67], v[90:91], v[82:83]
	v_lshl_add_u64 v[142:143], s[14:15], 0, v[72:73]
	v_lshlrev_b64 v[142:143], 2, v[142:143]
	v_lshl_add_u64 v[140:141], s[12:13], 0, v[142:143]
	v_lshl_add_u64 v[142:143], s[2:3], 0, v[142:143]
	global_load_dwordx4 v[118:121], v[140:141], off offset:784
	global_load_dwordx4 v[122:125], v[140:141], off offset:768
	global_load_dwordx4 v[126:129], v[142:143], off offset:784
	global_load_dwordx4 v[130:133], v[142:143], off offset:768
	s_mov_b64 s[6:7], 0x3000
	v_lshl_add_u64 v[142:143], v[142:143], 0, s[6:7]
	global_load_dwordx4 v[134:137], v[142:143], off offset:768
	global_load_dwordx4 v[138:141], v[142:143], off offset:784
	v_rcp_f32_e32 v53, v0
	v_add_f32_e32 v0, 1.0, v56
	v_rcp_f32_e32 v56, v0
	v_add_f32_e32 v0, 1.0, v57
	v_mul_f32_e32 v57, 0xbfb8aa3b, v66
	v_exp_f32_e32 v64, v57
	v_mul_f32_e32 v57, 0xbfb8aa3b, v67
	v_exp_f32_e32 v65, v57
	v_rcp_f32_e32 v57, v0
	v_add_f32_e32 v0, 1.0, v64
	v_rcp_f32_e32 v64, v0
	v_add_f32_e32 v0, 1.0, v65
	v_mul_f32_e32 v65, 0xbfb8aa3b, v60
	v_exp_f32_e32 v68, v65
	v_mul_f32_e32 v65, 0xbfb8aa3b, v61
	v_exp_f32_e32 v69, v65
	v_rcp_f32_e32 v65, v0
	v_add_f32_e32 v0, 1.0, v68
	v_rcp_f32_e32 v68, v0
	v_add_f32_e32 v0, 1.0, v69
	v_rcp_f32_e32 v69, v0
	v_pk_mul_f32 v[58:59], v[58:59], v[52:53]
	v_pk_mul_f32 v[56:57], v[62:63], v[56:57]
	v_pk_mul_f32 v[52:53], v[66:67], v[64:65]
	v_pk_mul_f32 v[60:61], v[60:61], v[68:69]
	v_lshlrev_b32_e32 v0, 1, v72
	s_cbranch_scc1 .LBB0_547
; DI unsigned pk2(float lo, float hi) { f32x2 v = {lo, hi}; bf16x2_t b = __builtin_convertvector(v, bf16x2_t); return __builtin_bit_cast(unsigned, b); }
; DI void conv_phase(PPtr p, int j, ldsp lds, int tid) {
;     ...
;             if (cb >= 8) { u32x4 w; w.x = pk2(acc[0], acc[1]); w.y = pk2(acc[2], acc[3]); w.z = pk2(acc[4], acc[5]); w.w = pk2(acc[6], acc[7]);
;                 bf16_t* dst = (cb < 10) ? Bc + (size_t)t * 512 + (cb - 8) * 256 + cl : Cc + (size_t)t * 512 + (cb - 10) * 256 + cl;
;                 *(u32x4*)dst = w; }
	v_cvt_pk_bf16_f32 v62, v58, v59
	v_cvt_pk_bf16_f32 v63, v56, v57
	v_cvt_pk_bf16_f32 v64, v52, v53
	v_cvt_pk_bf16_f32 v65, v60, v61
	v_lshl_add_u64 v[54:55], v[50:51], 0, v[0:1]
	global_store_dwordx4 v[54:55], v[62:65], off

; DI unsigned pk2(float lo, float hi) { f32x2 v = {lo, hi}; bf16x2_t b = __builtin_convertvector(v, bf16x2_t); return __builtin_bit_cast(unsigned, b); }
; DI float bflo(unsigned w) { return __uint_as_float(w << 16); }
; DI float bfhi(unsigned w) { return __uint_as_float(w & 0xffff0000u); }
; DI float silu_f(float g) { return g * __builtin_amdgcn_rcpf(1.0f + __expf(-g)); }
; DI void conv_phase(PPtr p, int j, ldsp lds, int tid) {
;     ...
;         for (int k = 0; k < 4; ++k) {
;             const int cl = (cgp + 8 * k) * 8, ch0 = cb * 256 + cl;
;             float acc[8];
;             { const f32x4 b0 = *(const f32x4*)(cbias + ch0), b1 = *(const f32x4*)(cbias + ch0 + 4);
; #pragma unroll
;               for (int i = 0; i < 4; ++i) { acc[i] = b0[i]; acc[4 + i] = b1[i]; } }
; #pragma unroll
;             for (int w = 0; w < 4; ++w) {
;                 const f32x4 w0 = *(const f32x4*)(cw + w * CONVD + ch0), w1 = *(const f32x4*)(cw + w * CONVD + ch0 + 4);
;                 const u32x4 uu = u[k][w];
;                 acc[0] += bflo(uu[0]) * w0[0]; acc[1] += bfhi(uu[0]) * w0[1]; acc[2] += bflo(uu[1]) * w0[2]; acc[3] += bfhi(uu[1]) * w0[3];
;                 acc[4] += bflo(uu[2]) * w1[0]; acc[5] += bfhi(uu[2]) * w1[1]; acc[6] += bflo(uu[3]) * w1[2]; acc[7] += bfhi(uu[3]) * w1[3];
;             }
; #pragma unroll
;             for (int i = 0; i < 8; ++i) acc[i] = silu_f(acc[i]);
;             if (cb >= 8) { u32x4 w; w.x = pk2(acc[0], acc[1]); w.y = pk2(acc[2], acc[3]); w.z = pk2(acc[4], acc[5]); w.w = pk2(acc[6], acc[7]);
;                 bf16_t* dst = (cb < 10) ? Bc + (size_t)t * 512 + (cb - 8) * 256 + cl : Cc + (size_t)t * 512 + (cb - 10) * 256 + cl;
;                 *(u32x4*)dst = w; }
.LBB0_549:
	s_ashr_i32 s15, s14, 31
	v_lshl_add_u64 v[52:53], s[14:15], 0, v[72:73]
	v_lshlrev_b64 v[52:53], 2, v[52:53]
	v_lshl_add_u64 v[54:55], s[12:13], 0, v[52:53]
	v_lshl_add_u64 v[52:53], s[2:3], 0, v[52:53]
	v_add_co_u32_e32 v82, vcc, 0x3000, v52
	s_mov_b64 s[0:1], 0x3100
	s_nop 0
	v_addc_co_u32_e32 v83, vcc, 0, v53, vcc
	s_waitcnt vmcnt(20)
	v_mov_b32_e32 v56, v144
	v_mov_b32_e32 v57, v145
	v_mov_b32_e32 v58, v146
	v_mov_b32_e32 v59, v147
	v_mov_b32_e32 v60, v148
	v_mov_b32_e32 v61, v149
	v_mov_b32_e32 v62, v150
	v_mov_b32_e32 v63, v151
	v_mov_b32_e32 v64, v156
	v_mov_b32_e32 v65, v157
	v_mov_b32_e32 v66, v158
	v_mov_b32_e32 v67, v159
	v_mov_b32_e32 v90, v160
	v_mov_b32_e32 v91, v161
	v_mov_b32_e32 v92, v162
	v_mov_b32_e32 v93, v163
	v_lshl_add_u64 v[68:69], v[52:53], 0, s[0:1]
	v_mov_b32_e32 v94, v164
	v_mov_b32_e32 v95, v165
	v_mov_b32_e32 v96, v166
	v_mov_b32_e32 v97, v167
	v_mov_b32_e32 v98, v168
	v_mov_b32_e32 v99, v169
	v_mov_b32_e32 v100, v170
	v_mov_b32_e32 v101, v171
	v_add_co_u32_e32 v82, vcc, 0x6000, v52
	s_mov_b64 s[0:1], 0x6100
	s_nop 0
	v_addc_co_u32_e32 v83, vcc, 0, v53, vcc
	v_lshl_add_u64 v[68:69], v[52:53], 0, s[0:1]
	v_mov_b32_e32 v102, v172
	v_mov_b32_e32 v103, v173
	v_mov_b32_e32 v104, v174
	v_mov_b32_e32 v105, v175
	v_mov_b32_e32 v106, v176
	v_mov_b32_e32 v107, v177
	v_mov_b32_e32 v108, v178
	v_mov_b32_e32 v109, v179
	v_add_co_u32_e32 v82, vcc, 0x9000, v52
	s_mov_b64 s[0:1], 0x9100
	s_nop 0
	v_addc_co_u32_e32 v83, vcc, 0, v53, vcc
	v_lshl_add_u64 v[68:69], v[52:53], 0, s[0:1]
	v_mov_b32_e32 v110, v180
	v_mov_b32_e32 v111, v181
	v_mov_b32_e32 v112, v182
	v_mov_b32_e32 v113, v183
	v_mov_b32_e32 v114, v184
	v_mov_b32_e32 v115, v185
	v_mov_b32_e32 v116, v186
	v_mov_b32_e32 v117, v187
	v_lshlrev_b32_e32 v68, 16, v38
	v_and_b32_e32 v69, 0xffff0000, v38
	v_lshlrev_b32_e32 v38, 16, v39
	v_and_b32_e32 v39, 0xffff0000, v39
	s_andn2_b64 vcc, exec, s[4:5]
	v_pk_fma_f32 v[60:61], v[90:91], v[68:69], v[60:61]
	v_lshlrev_b32_e32 v68, 16, v34
	v_and_b32_e32 v69, 0xffff0000, v34
	v_pk_fma_f32 v[38:39], v[92:93], v[38:39], v[62:63]
	v_lshlrev_b32_e32 v34, 16, v35
	v_and_b32_e32 v35, 0xffff0000, v35
	v_pk_fma_f32 v[34:35], v[96:97], v[34:35], v[38:39]
	v_lshlrev_b32_e32 v38, 16, v47
	v_and_b32_e32 v39, 0xffff0000, v47
	v_pk_fma_f32 v[60:61], v[94:95], v[68:69], v[60:61]
	v_lshlrev_b32_e32 v68, 16, v46
	v_and_b32_e32 v69, 0xffff0000, v46
	v_pk_fma_f32 v[34:35], v[104:105], v[38:39], v[34:35]
	v_lshlrev_b32_e32 v38, 16, v43
	v_and_b32_e32 v39, 0xffff0000, v43
	v_pk_fma_f32 v[60:61], v[102:103], v[68:69], v[60:61]
	v_lshlrev_b32_e32 v68, 16, v42
	v_and_b32_e32 v69, 0xffff0000, v42
	v_pk_fma_f32 v[42:43], v[112:113], v[38:39], v[34:35]
	v_lshlrev_b32_e32 v34, 16, v40
	v_and_b32_e32 v35, 0xffff0000, v40
	v_pk_fma_f32 v[34:35], v[64:65], v[34:35], v[56:57]
	v_lshlrev_b32_e32 v38, 16, v36
	v_and_b32_e32 v39, 0xffff0000, v36
	v_pk_fma_f32 v[34:35], v[98:99], v[38:39], v[34:35]
	v_lshlrev_b32_e32 v38, 16, v48
	v_and_b32_e32 v39, 0xffff0000, v48
	v_pk_fma_f32 v[34:35], v[106:107], v[38:39], v[34:35]
	v_lshlrev_b32_e32 v38, 16, v44
	v_and_b32_e32 v39, 0xffff0000, v44
	v_pk_fma_f32 v[34:35], v[114:115], v[38:39], v[34:35]
	v_lshlrev_b32_e32 v38, 16, v41
	v_and_b32_e32 v39, 0xffff0000, v41
	v_mul_f32_e32 v40, 0xbfb8aa3b, v42
	v_mul_f32_e32 v41, 0xbfb8aa3b, v43
	v_exp_f32_e32 v40, v40
	v_exp_f32_e32 v41, v41
	v_pk_fma_f32 v[38:39], v[66:67], v[38:39], v[58:59]
	v_lshlrev_b32_e32 v36, 16, v37
	v_add_f32_e32 v40, 1.0, v40
	v_add_f32_e32 v41, 1.0, v41
	v_rcp_f32_e32 v40, v40
	v_rcp_f32_e32 v41, v41
	v_and_b32_e32 v37, 0xffff0000, v37
	v_pk_fma_f32 v[36:37], v[100:101], v[36:37], v[38:39]
	v_lshlrev_b32_e32 v38, 16, v49
	v_pk_mul_f32 v[40:41], v[42:43], v[40:41]
	v_mul_f32_e32 v42, 0xbfb8aa3b, v34
	v_mul_f32_e32 v43, 0xbfb8aa3b, v35
	v_exp_f32_e32 v42, v42
	v_exp_f32_e32 v43, v43
	v_and_b32_e32 v39, 0xffff0000, v49
	v_pk_fma_f32 v[36:37], v[108:109], v[38:39], v[36:37]
	v_add_f32_e32 v42, 1.0, v42
	v_add_f32_e32 v43, 1.0, v43
	v_rcp_f32_e32 v42, v42
	v_rcp_f32_e32 v43, v43
	v_lshlrev_b32_e32 v38, 16, v45
	v_and_b32_e32 v39, 0xffff0000, v45
	v_pk_fma_f32 v[36:37], v[116:117], v[38:39], v[36:37]
	v_pk_fma_f32 v[60:61], v[110:111], v[68:69], v[60:61]
	v_pk_mul_f32 v[34:35], v[34:35], v[42:43]
	v_mul_f32_e32 v42, 0xbfb8aa3b, v36
	v_mul_f32_e32 v43, 0xbfb8aa3b, v37
	v_mul_f32_e32 v38, 0xbfb8aa3b, v60
	v_mul_f32_e32 v39, 0xbfb8aa3b, v61
	v_exp_f32_e32 v42, v42
	v_exp_f32_e32 v43, v43
	v_exp_f32_e32 v38, v38
	v_exp_f32_e32 v39, v39
	v_add_f32_e32 v42, 1.0, v42
	v_add_f32_e32 v43, 1.0, v43
	v_add_f32_e32 v38, 1.0, v38
	v_add_f32_e32 v39, 1.0, v39
	v_rcp_f32_e32 v42, v42
	v_rcp_f32_e32 v43, v43
	v_rcp_f32_e32 v38, v38
	v_rcp_f32_e32 v39, v39
	v_pk_mul_f32 v[36:37], v[36:37], v[42:43]
	v_cndmask_b32_e64 v42, 0, 1, s[4:5]
	v_pk_mul_f32 v[38:39], v[60:61], v[38:39]
	v_cmp_ne_u32_e64 s[0:1], 1, v42
	s_cbranch_vccnz .LBB0_551
	v_cvt_pk_bf16_f32 v42, v38, v39
	v_cvt_pk_bf16_f32 v43, v40, v41
	v_cvt_pk_bf16_f32 v44, v34, v35
	v_cvt_pk_bf16_f32 v45, v36, v37
	v_lshl_add_u64 v[46:47], v[50:51], 0, v[0:1]
	global_store_dwordx4 v[46:47], v[42:45], off offset:128

; DI unsigned pk2(float lo, float hi) { f32x2 v = {lo, hi}; bf16x2_t b = __builtin_convertvector(v, bf16x2_t); return __builtin_bit_cast(unsigned, b); }
; DI float bflo(unsigned w) { return __uint_as_float(w << 16); }
; DI float bfhi(unsigned w) { return __uint_as_float(w & 0xffff0000u); }
; DI float silu_f(float g) { return g * __builtin_amdgcn_rcpf(1.0f + __expf(-g)); }
; DI void conv_phase(PPtr p, int j, ldsp lds, int tid) {
;     ...
;         for (int k = 0; k < 4; ++k) {
;             const int cl = (cgp + 8 * k) * 8, ch0 = cb * 256 + cl;
;             float acc[8];
;             { const f32x4 b0 = *(const f32x4*)(cbias + ch0), b1 = *(const f32x4*)(cbias + ch0 + 4);
; #pragma unroll
;               for (int i = 0; i < 4; ++i) { acc[i] = b0[i]; acc[4 + i] = b1[i]; } }
; #pragma unroll
;             for (int w = 0; w < 4; ++w) {
;                 const f32x4 w0 = *(const f32x4*)(cw + w * CONVD + ch0), w1 = *(const f32x4*)(cw + w * CONVD + ch0 + 4);
;                 const u32x4 uu = u[k][w];
;                 acc[0] += bflo(uu[0]) * w0[0]; acc[1] += bfhi(uu[0]) * w0[1]; acc[2] += bflo(uu[1]) * w0[2]; acc[3] += bfhi(uu[1]) * w0[3];
;                 acc[4] += bflo(uu[2]) * w1[0]; acc[5] += bfhi(uu[2]) * w1[1]; acc[6] += bflo(uu[3]) * w1[2]; acc[7] += bfhi(uu[3]) * w1[3];
;             }
; #pragma unroll
;             for (int i = 0; i < 8; ++i) acc[i] = silu_f(acc[i]);
;             if (cb >= 8) { u32x4 w; w.x = pk2(acc[0], acc[1]); w.y = pk2(acc[2], acc[3]); w.z = pk2(acc[4], acc[5]); w.w = pk2(acc[6], acc[7]);
;                 bf16_t* dst = (cb < 10) ? Bc + (size_t)t * 512 + (cb - 8) * 256 + cl : Cc + (size_t)t * 512 + (cb - 10) * 256 + cl;
;                 *(u32x4*)dst = w; }
.LBB0_553:
	v_add_co_u32_e32 v56, vcc, 0x3000, v52
	s_waitcnt vmcnt(10)
	v_mov_b32_e32 v34, v188
	v_mov_b32_e32 v35, v189
	v_mov_b32_e32 v36, v190
	v_mov_b32_e32 v37, v191
	v_mov_b32_e32 v38, v192
	v_mov_b32_e32 v39, v193
	v_mov_b32_e32 v40, v194
	v_mov_b32_e32 v41, v195
	v_mov_b32_e32 v42, v196
	v_mov_b32_e32 v43, v197
	v_mov_b32_e32 v44, v198
	v_mov_b32_e32 v45, v199
	v_mov_b32_e32 v46, v206
	v_mov_b32_e32 v47, v207
	v_mov_b32_e32 v48, v208
	v_mov_b32_e32 v49, v209
	v_addc_co_u32_e32 v57, vcc, 0, v53, vcc
	s_mov_b64 s[6:7], 0x3200
	v_add_co_u32_e32 v64, vcc, 0x6000, v52
	v_lshl_add_u64 v[60:61], v[52:53], 0, s[6:7]
	s_nop 0
	v_addc_co_u32_e32 v65, vcc, 0, v53, vcc
	v_mov_b32_e32 v56, v210
	v_mov_b32_e32 v57, v211
	v_mov_b32_e32 v58, v212
	v_mov_b32_e32 v59, v213
	s_nop 0
	v_mov_b32_e32 v60, v218
	v_mov_b32_e32 v61, v219
	v_mov_b32_e32 v62, v220
	v_mov_b32_e32 v63, v221
	s_mov_b64 s[6:7], 0x6200
	v_add_co_u32_e32 v82, vcc, 0x9000, v52
	v_lshl_add_u64 v[68:69], v[52:53], 0, s[6:7]
	v_mov_b32_e32 v64, v222
	v_mov_b32_e32 v65, v223
	v_mov_b32_e32 v66, v224
	v_mov_b32_e32 v67, v225
	s_nop 0
	v_mov_b32_e32 v90, v226
	v_mov_b32_e32 v91, v227
	v_mov_b32_e32 v92, v228
	v_mov_b32_e32 v93, v229
	s_mov_b64 s[6:7], 0x9200
	v_addc_co_u32_e32 v83, vcc, 0, v53, vcc
	v_lshl_add_u64 v[68:69], v[52:53], 0, s[6:7]
	v_mov_b32_e32 v94, v230
	v_mov_b32_e32 v95, v231
	v_mov_b32_e32 v96, v232
	v_mov_b32_e32 v97, v233
	v_mov_b32_e32 v98, v234
	v_mov_b32_e32 v99, v235
	v_mov_b32_e32 v100, v236
	v_mov_b32_e32 v101, v237
	v_lshlrev_b32_e32 v68, 16, v22
	v_and_b32_e32 v69, 0xffff0000, v22
	v_lshlrev_b32_e32 v22, 16, v23
	v_and_b32_e32 v23, 0xffff0000, v23
	s_and_b64 vcc, exec, s[0:1]
	v_pk_fma_f32 v[38:39], v[46:47], v[68:69], v[38:39]
	v_lshlrev_b32_e32 v46, 16, v18
	v_and_b32_e32 v47, 0xffff0000, v18
	v_pk_fma_f32 v[22:23], v[48:49], v[22:23], v[40:41]
	v_lshlrev_b32_e32 v18, 16, v19
	v_and_b32_e32 v19, 0xffff0000, v19
	v_pk_fma_f32 v[18:19], v[58:59], v[18:19], v[22:23]
	v_lshlrev_b32_e32 v22, 16, v31
	v_and_b32_e32 v23, 0xffff0000, v31
	v_pk_fma_f32 v[38:39], v[56:57], v[46:47], v[38:39]
	v_lshlrev_b32_e32 v46, 16, v30
	v_pk_fma_f32 v[18:19], v[66:67], v[22:23], v[18:19]
	v_lshlrev_b32_e32 v22, 16, v27
	v_and_b32_e32 v23, 0xffff0000, v27
	v_and_b32_e32 v47, 0xffff0000, v30
	v_pk_fma_f32 v[38:39], v[64:65], v[46:47], v[38:39]
	v_pk_fma_f32 v[22:23], v[96:97], v[22:23], v[18:19]
	v_lshlrev_b32_e32 v18, 16, v24
	v_and_b32_e32 v19, 0xffff0000, v24
	v_lshlrev_b32_e32 v46, 16, v26
	v_and_b32_e32 v47, 0xffff0000, v26
	v_pk_fma_f32 v[18:19], v[42:43], v[18:19], v[34:35]
	v_lshlrev_b32_e32 v26, 16, v20
	v_and_b32_e32 v27, 0xffff0000, v20
	v_pk_fma_f32 v[18:19], v[60:61], v[26:27], v[18:19]
	v_lshlrev_b32_e32 v26, 16, v32
	v_and_b32_e32 v27, 0xffff0000, v32
	v_pk_fma_f32 v[18:19], v[90:91], v[26:27], v[18:19]
	v_lshlrev_b32_e32 v26, 16, v28
	v_and_b32_e32 v27, 0xffff0000, v28
	v_pk_fma_f32 v[18:19], v[98:99], v[26:27], v[18:19]
	v_mul_f32_e32 v26, 0xbfb8aa3b, v22
	v_mul_f32_e32 v27, 0xbfb8aa3b, v23
	v_exp_f32_e32 v26, v26
	v_exp_f32_e32 v27, v27
	v_lshlrev_b32_e32 v24, 16, v25
	v_and_b32_e32 v25, 0xffff0000, v25
	v_add_f32_e32 v26, 1.0, v26
	v_add_f32_e32 v27, 1.0, v27
	v_rcp_f32_e32 v26, v26
	v_rcp_f32_e32 v27, v27
	v_pk_fma_f32 v[24:25], v[44:45], v[24:25], v[36:37]
	v_lshlrev_b32_e32 v20, 16, v21
	v_and_b32_e32 v21, 0xffff0000, v21
	v_pk_mul_f32 v[22:23], v[22:23], v[26:27]
	v_mul_f32_e32 v26, 0xbfb8aa3b, v18
	v_mul_f32_e32 v27, 0xbfb8aa3b, v19
	v_exp_f32_e32 v26, v26
	v_exp_f32_e32 v27, v27
	v_pk_fma_f32 v[20:21], v[62:63], v[20:21], v[24:25]
	v_lshlrev_b32_e32 v24, 16, v33
	v_add_f32_e32 v26, 1.0, v26
	v_add_f32_e32 v27, 1.0, v27
	v_rcp_f32_e32 v26, v26
	v_rcp_f32_e32 v27, v27
	v_and_b32_e32 v25, 0xffff0000, v33
	v_pk_fma_f32 v[20:21], v[92:93], v[24:25], v[20:21]
	v_lshlrev_b32_e32 v24, 16, v29
	v_and_b32_e32 v25, 0xffff0000, v29
	v_pk_fma_f32 v[38:39], v[94:95], v[46:47], v[38:39]
	v_pk_fma_f32 v[24:25], v[100:101], v[24:25], v[20:21]
	v_mul_f32_e32 v20, 0xbfb8aa3b, v38
	v_mul_f32_e32 v21, 0xbfb8aa3b, v39
	v_pk_mul_f32 v[18:19], v[18:19], v[26:27]
	v_mul_f32_e32 v26, 0xbfb8aa3b, v24
	v_mul_f32_e32 v27, 0xbfb8aa3b, v25
	v_exp_f32_e32 v20, v20
	v_exp_f32_e32 v21, v21
	v_exp_f32_e32 v26, v26
	v_exp_f32_e32 v27, v27
	v_add_f32_e32 v20, 1.0, v20
	v_add_f32_e32 v21, 1.0, v21
	v_add_f32_e32 v26, 1.0, v26
	v_add_f32_e32 v27, 1.0, v27
	v_rcp_f32_e32 v20, v20
	v_rcp_f32_e32 v21, v21
	v_rcp_f32_e32 v26, v26
	v_rcp_f32_e32 v27, v27
	v_pk_mul_f32 v[20:21], v[38:39], v[20:21]
	v_pk_mul_f32 v[24:25], v[24:25], v[26:27]
	s_cbranch_vccnz .LBB0_555
	v_cvt_pk_bf16_f32 v26, v20, v21
	v_cvt_pk_bf16_f32 v27, v22, v23
	v_cvt_pk_bf16_f32 v28, v18, v19
	v_cvt_pk_bf16_f32 v29, v24, v25
	v_lshl_add_u64 v[30:31], v[50:51], 0, v[0:1]
	global_store_dwordx4 v[30:31], v[26:29], off offset:256

; DI unsigned pk2(float lo, float hi) { f32x2 v = {lo, hi}; bf16x2_t b = __builtin_convertvector(v, bf16x2_t); return __builtin_bit_cast(unsigned, b); }
; DI float bflo(unsigned w) { return __uint_as_float(w << 16); }
; DI float bfhi(unsigned w) { return __uint_as_float(w & 0xffff0000u); }
; DI float silu_f(float g) { return g * __builtin_amdgcn_rcpf(1.0f + __expf(-g)); }
; DI void conv_phase(PPtr p, int j, ldsp lds, int tid) {
;     ...
;         for (int k = 0; k < 4; ++k) {
;             const int cl = (cgp + 8 * k) * 8, ch0 = cb * 256 + cl;
;             float acc[8];
;             { const f32x4 b0 = *(const f32x4*)(cbias + ch0), b1 = *(const f32x4*)(cbias + ch0 + 4);
; #pragma unroll
;               for (int i = 0; i < 4; ++i) { acc[i] = b0[i]; acc[4 + i] = b1[i]; } }
; #pragma unroll
;             for (int w = 0; w < 4; ++w) {
;                 const f32x4 w0 = *(const f32x4*)(cw + w * CONVD + ch0), w1 = *(const f32x4*)(cw + w * CONVD + ch0 + 4);
;                 const u32x4 uu = u[k][w];
;                 acc[0] += bflo(uu[0]) * w0[0]; acc[1] += bfhi(uu[0]) * w0[1]; acc[2] += bflo(uu[1]) * w0[2]; acc[3] += bfhi(uu[1]) * w0[3];
;                 acc[4] += bflo(uu[2]) * w1[0]; acc[5] += bfhi(uu[2]) * w1[1]; acc[6] += bflo(uu[3]) * w1[2]; acc[7] += bfhi(uu[3]) * w1[3];
;             }
; #pragma unroll
;             for (int i = 0; i < 8; ++i) acc[i] = silu_f(acc[i]);
;             if (cb >= 8) { u32x4 w; w.x = pk2(acc[0], acc[1]); w.y = pk2(acc[2], acc[3]); w.z = pk2(acc[4], acc[5]); w.w = pk2(acc[6], acc[7]);
;                 bf16_t* dst = (cb < 10) ? Bc + (size_t)t * 512 + (cb - 8) * 256 + cl : Cc + (size_t)t * 512 + (cb - 10) * 256 + cl;
;                 *(u32x4*)dst = w; }
.LBB0_557:
	v_add_co_u32_e32 v34, vcc, 0x3000, v52
	s_mov_b64 s[6:7], 0x3300
	s_nop 0
	v_addc_co_u32_e32 v35, vcc, 0, v53, vcc
	s_waitcnt vmcnt(0)
	v_mov_b32_e32 v18, v118
	v_mov_b32_e32 v19, v119
	v_mov_b32_e32 v20, v120
	v_mov_b32_e32 v21, v121
	v_mov_b32_e32 v22, v122
	v_mov_b32_e32 v23, v123
	v_mov_b32_e32 v24, v124
	v_mov_b32_e32 v25, v125
	v_mov_b32_e32 v26, v126
	v_mov_b32_e32 v27, v127
	v_mov_b32_e32 v28, v128
	v_mov_b32_e32 v29, v129
	v_mov_b32_e32 v30, v130
	v_mov_b32_e32 v31, v131
	v_mov_b32_e32 v32, v132
	v_mov_b32_e32 v33, v133
	v_lshl_add_u64 v[38:39], v[52:53], 0, s[6:7]
	s_mov_b64 s[6:7], 0x6300
	v_add_co_u32_e32 v42, vcc, 0x6000, v52
	v_lshl_add_u64 v[46:47], v[52:53], 0, s[6:7]
	s_nop 0
	v_addc_co_u32_e32 v43, vcc, 0, v53, vcc
	s_mov_b64 s[6:7], 0x9300
	v_mov_b32_e32 v34, v134
	v_mov_b32_e32 v35, v135
	v_mov_b32_e32 v36, v136
	v_mov_b32_e32 v37, v137
	s_nop 0
	v_mov_b32_e32 v38, v138
	v_mov_b32_e32 v39, v139
	v_mov_b32_e32 v40, v140
	v_mov_b32_e32 v41, v141
	v_lshl_add_u64 v[56:57], v[52:53], 0, s[6:7]
	v_add_co_u32_e32 v52, vcc, 0x9000, v52
	v_mov_b32_e32 v42, v238
	v_mov_b32_e32 v43, v239
	v_mov_b32_e32 v44, v240
	v_mov_b32_e32 v45, v241
	s_nop 0
	v_mov_b32_e32 v46, v242
	v_mov_b32_e32 v47, v243
	v_mov_b32_e32 v48, v244
	v_mov_b32_e32 v49, v245
	v_addc_co_u32_e32 v53, vcc, 0, v53, vcc
	v_mov_b32_e32 v52, v246
	v_mov_b32_e32 v53, v247
	v_mov_b32_e32 v54, v248
	v_mov_b32_e32 v55, v249
	s_nop 0
	v_mov_b32_e32 v56, v250
	v_mov_b32_e32 v57, v251
	v_mov_b32_e32 v58, v252
	v_mov_b32_e32 v59, v253
	v_lshlrev_b32_e32 v60, 16, v6
	v_and_b32_e32 v61, 0xffff0000, v6
	v_lshlrev_b32_e32 v6, 16, v7
	v_and_b32_e32 v7, 0xffff0000, v7
	s_and_b64 vcc, exec, s[0:1]
	s_waitcnt vmcnt(6)
	v_pk_fma_f32 v[22:23], v[30:31], v[60:61], v[22:23]
	v_lshlrev_b32_e32 v30, 16, v2
	v_and_b32_e32 v31, 0xffff0000, v2
	v_pk_fma_f32 v[6:7], v[32:33], v[6:7], v[24:25]
	v_lshlrev_b32_e32 v2, 16, v3
	v_and_b32_e32 v3, 0xffff0000, v3
	s_waitcnt vmcnt(5)
	v_pk_fma_f32 v[2:3], v[36:37], v[2:3], v[6:7]
	v_lshlrev_b32_e32 v6, 16, v15
	v_and_b32_e32 v7, 0xffff0000, v15
	v_pk_fma_f32 v[22:23], v[34:35], v[30:31], v[22:23]
	s_waitcnt vmcnt(3)
	v_pk_fma_f32 v[2:3], v[44:45], v[6:7], v[2:3]
	v_lshlrev_b32_e32 v6, 16, v11
	v_and_b32_e32 v7, 0xffff0000, v11
	v_lshlrev_b32_e32 v30, 16, v14
	v_and_b32_e32 v31, 0xffff0000, v14
	s_waitcnt vmcnt(1)
	v_pk_fma_f32 v[6:7], v[54:55], v[6:7], v[2:3]
	v_lshlrev_b32_e32 v2, 16, v8
	v_and_b32_e32 v3, 0xffff0000, v8
	v_pk_fma_f32 v[22:23], v[42:43], v[30:31], v[22:23]
	v_lshlrev_b32_e32 v30, 16, v10
	v_and_b32_e32 v31, 0xffff0000, v10
	v_pk_fma_f32 v[2:3], v[26:27], v[2:3], v[18:19]
	v_lshlrev_b32_e32 v10, 16, v4
	v_and_b32_e32 v11, 0xffff0000, v4
	v_pk_fma_f32 v[2:3], v[38:39], v[10:11], v[2:3]
	v_lshlrev_b32_e32 v10, 16, v16
	v_and_b32_e32 v11, 0xffff0000, v16
	v_pk_fma_f32 v[2:3], v[46:47], v[10:11], v[2:3]
	v_lshlrev_b32_e32 v10, 16, v12
	v_and_b32_e32 v11, 0xffff0000, v12
	s_waitcnt vmcnt(0)
	v_pk_fma_f32 v[2:3], v[56:57], v[10:11], v[2:3]
	v_mul_f32_e32 v10, 0xbfb8aa3b, v6
	v_mul_f32_e32 v11, 0xbfb8aa3b, v7
	v_exp_f32_e32 v10, v10
	v_exp_f32_e32 v11, v11
	v_lshlrev_b32_e32 v8, 16, v9
	v_and_b32_e32 v9, 0xffff0000, v9
	v_add_f32_e32 v10, 1.0, v10
	v_add_f32_e32 v11, 1.0, v11
	v_rcp_f32_e32 v10, v10
	v_rcp_f32_e32 v11, v11
	v_pk_fma_f32 v[8:9], v[28:29], v[8:9], v[20:21]
	v_lshlrev_b32_e32 v4, 16, v5
	v_and_b32_e32 v5, 0xffff0000, v5
	v_pk_mul_f32 v[6:7], v[6:7], v[10:11]
	v_mul_f32_e32 v10, 0xbfb8aa3b, v2
	v_mul_f32_e32 v11, 0xbfb8aa3b, v3
	v_exp_f32_e32 v10, v10
	v_exp_f32_e32 v11, v11
	v_pk_fma_f32 v[4:5], v[40:41], v[4:5], v[8:9]
	v_lshlrev_b32_e32 v8, 16, v17
	v_add_f32_e32 v10, 1.0, v10
	v_add_f32_e32 v11, 1.0, v11
	v_rcp_f32_e32 v10, v10
	v_rcp_f32_e32 v11, v11
	v_and_b32_e32 v9, 0xffff0000, v17
	v_pk_fma_f32 v[4:5], v[48:49], v[8:9], v[4:5]
	v_lshlrev_b32_e32 v8, 16, v13
	v_and_b32_e32 v9, 0xffff0000, v13
	v_pk_fma_f32 v[22:23], v[52:53], v[30:31], v[22:23]
	v_pk_fma_f32 v[8:9], v[58:59], v[8:9], v[4:5]
	v_mul_f32_e32 v4, 0xbfb8aa3b, v22
	v_mul_f32_e32 v5, 0xbfb8aa3b, v23
	v_pk_mul_f32 v[2:3], v[2:3], v[10:11]
	v_mul_f32_e32 v10, 0xbfb8aa3b, v8
	v_mul_f32_e32 v11, 0xbfb8aa3b, v9
	v_exp_f32_e32 v4, v4
	v_exp_f32_e32 v5, v5
	v_exp_f32_e32 v10, v10
	v_exp_f32_e32 v11, v11
	v_add_f32_e32 v4, 1.0, v4
	v_add_f32_e32 v5, 1.0, v5
	v_add_f32_e32 v10, 1.0, v10
	v_add_f32_e32 v11, 1.0, v11
	v_rcp_f32_e32 v4, v4
	v_rcp_f32_e32 v5, v5
	v_rcp_f32_e32 v10, v10
	v_rcp_f32_e32 v11, v11
	v_pk_mul_f32 v[4:5], v[22:23], v[4:5]
	v_pk_mul_f32 v[8:9], v[8:9], v[10:11]
	s_cbranch_vccnz .LBB0_559
	v_cvt_pk_bf16_f32 v10, v4, v5
	v_cvt_pk_bf16_f32 v11, v6, v7
	v_cvt_pk_bf16_f32 v12, v2, v3
	v_cvt_pk_bf16_f32 v13, v8, v9
	v_lshl_add_u64 v[14:15], v[50:51], 0, v[0:1]
	global_store_dwordx4 v[14:15], v[10:13], off offset:384
	s_and_b64 vcc, exec, s[4:5]
	s_cbranch_vccnz .LBB0_512
	s_branch .LBB0_560
